# phase3 rebalance: k_nope tiles moved to workgroups 128-255 (each runs 2), workgroups 0-127 skip k_nope since they run 2 q-up tiles
# baseline (speedup 1.0000x reference)
;     __device__ __forceinline__ bool next(int i, Unit& u) const { if (!base.next(i >> 2, u)) return false; u.kind = i & 3; return true; }
;     __device__ __forceinline__ bool next(int i, Unit& u) const {
;         const long L = (long)i * G + c; if (L >= nwg) return false;
;         int wgid = (int)L; { const int q = nwg / NXCD, r = nwg % NXCD, xcd = wgid % NXCD; int off = wgid / NXCD;
;             if (rev) off = (xcd < r ? q : q - 1) - off;
;             wgid = (xcd < r ? xcd * (q + 1) : r * (q + 1) + (xcd - r) * q) + off; }
;         const int nig = WGM * nN, gid = wgid / nig, fm = gid * WGM, gsz = (nM - fm) < WGM ? (nM - fm) : WGM;
;         u.pm = fm + ((wgid % nig) % gsz); u.pn = (wgid % nig) / gsz; u.kind = 0; return true;
; __global__ void __launch_bounds__(512, 2) mk_fwd(Args args) {
;     ...
;             { pg8::Gemm g{PA + 1024, Wb + WO_KN, PA_LD, 256, 256}; pg8::StaticOrder S; S.init(TOK, 512, G, bx); pg8::EpiKnope E{Kb, lssq}; pg8::gemm_phase(lds, g, S, E); }
.LBB0_479:
	s_add_u32 s12, s50, 0x12000800
	s_addc_u32 s13, s51, 0
	v_mov_b32_e32 v0, v222
	s_cmpk_lt_i32 s2, 0x100
	s_movk_i32 s21, 0x100
	v_readfirstlane_b32 s20, v0
	s_cselect_b64 s[24:25], -1, 0
	s_mov_b32 s0, 0
	v_writelane_b32 v255, s0, 11
	s_cmpk_lg_i32 s35, 0x100
	s_cbranch_scc1 .Lkn_go
	s_cmpk_lt_i32 s2, 0x80
	s_cbranch_scc1 .LBB0_506
	s_mov_b32 s0, 1
	v_writelane_b32 v255, s0, 11
	s_sub_i32 s2, s2, 0x80
	s_movk_i32 s35, 0x80
.Lkn_go:
	s_cmpk_gt_i32 s2, 0xff
	s_cbranch_scc1 .LBB0_506
	s_ashr_i32 s14, s2, 31
	s_lshr_b32 s0, s14, 29
	s_add_i32 s15, s2, s0
	s_and_b32 s0, s15, -8
	s_sub_i32 s16, s2, s0
	s_cmp_gt_i32 s16, -1
	s_mov_b64 s[0:1], -1
	s_cbranch_scc0 .LBB0_482
	s_lshl_b32 s19, s16, 5
	s_mov_b64 s[0:1], 0

; __global__ void __launch_bounds__(512, 2) mk_fwd(Args args) {
;     ...
;             { pg8::Gemm g{PA + 1024, Wb + WO_KN, PA_LD, 256, 256}; pg8::StaticOrder S; S.init(TOK, 512, G, bx); pg8::EpiKnope E{Kb, lssq}; pg8::gemm_phase(lds, g, S, E); }
.LBB0_506:
	v_readlane_b32 s31, v255, 11
	s_cmp_eq_u32 s31, 1
	s_cbranch_scc0 .Lkn_done
	s_add_i32 s2, s2, 0x80
	s_movk_i32 s35, 0x100
